# all epilogue/conv de-serialisations + DIFF loop K-early/V-double-buffer/staging-under-PV
# baseline (speedup 1.0000x reference)
.LBB0_165:
	v_lshlrev_b32_e32 v0, 16, v211
	v_mul_f32_e32 v0, 0xbfb8aa3b, v0
	v_exp_f32_e32 v0, v0
	v_add_f32_e32 v2, v217, v219
	v_rcp_f32_e32 v2, v2
	ds_bpermute_b32 v3, v218, v183
	v_add_f32_e32 v0, 1.0, v0
	v_rcp_f32_e32 v0, v0
	v_lshl_add_u64 v[24:25], v[180:181], 1, s[22:23]
	s_lshl_b32 s80, s38, 1
	s_waitcnt lgkmcnt(0)
	v_add_f32_e32 v3, v183, v3
	v_mul_f32_e32 v0, v0, v2
	v_and_b32_e32 v2, 0xffff0000, v211
	v_mul_f32_e32 v2, 0xbfb8aa3b, v2
	v_exp_f32_e32 v2, v2
	v_rcp_f32_e32 v3, v3
	v_lshl_add_u64 v[24:25], v[24:25], 0, s[80:81]
	s_mov_b64 s[0:1], 0
	v_add_f32_e32 v2, 1.0, v2
	v_rcp_f32_e32 v2, v2
	s_nop 0
	v_mul_f32_e32 v2, v2, v3
	v_pk_mul_f32 v[4:5], v[82:83], v[2:3] op_sel_hi:[1,0]
	v_pk_mul_f32 v[8:9], v[86:87], v[2:3] op_sel_hi:[1,0]
	v_pk_mul_f32 v[10:11], v[88:89], v[2:3] op_sel_hi:[1,0]
	v_pk_mul_f32 v[12:13], v[90:91], v[2:3] op_sel_hi:[1,0]
	v_pk_mul_f32 v[14:15], v[92:93], v[2:3] op_sel_hi:[1,0]
	v_pk_mul_f32 v[16:17], v[94:95], v[2:3] op_sel_hi:[1,0]
	v_pk_mul_f32 v[18:19], v[96:97], v[2:3] op_sel_hi:[1,0]
	v_pk_mul_f32 v[6:7], v[84:85], v[2:3] op_sel_hi:[1,0]
	v_pk_fma_f32 v[20:21], v[48:49], v[0:1], v[18:19] op_sel_hi:[1,0,1]
	v_pk_fma_f32 v[22:23], v[46:47], v[0:1], v[16:17] op_sel_hi:[1,0,1]
	v_pk_fma_f32 v[26:27], v[44:45], v[0:1], v[14:15] op_sel_hi:[1,0,1]
	v_pk_fma_f32 v[28:29], v[42:43], v[0:1], v[12:13] op_sel_hi:[1,0,1]
	v_pk_fma_f32 v[30:31], v[40:41], v[0:1], v[10:11] op_sel_hi:[1,0,1]
	v_pk_fma_f32 v[32:33], v[38:39], v[0:1], v[8:9] op_sel_hi:[1,0,1]
	v_pk_fma_f32 v[34:35], v[34:35], v[0:1], v[4:5] op_sel_hi:[1,0,1]
	v_pk_mul_f32 v[18:19], v[66:67], v[2:3] op_sel_hi:[1,0]
	v_pk_mul_f32 v[16:17], v[68:69], v[2:3] op_sel_hi:[1,0]
	v_pk_mul_f32 v[14:15], v[70:71], v[2:3] op_sel_hi:[1,0]
	v_pk_mul_f32 v[12:13], v[72:73], v[2:3] op_sel_hi:[1,0]
	v_pk_mul_f32 v[10:11], v[74:75], v[2:3] op_sel_hi:[1,0]
	v_pk_mul_f32 v[8:9], v[76:77], v[2:3] op_sel_hi:[1,0]
	v_pk_mul_f32 v[4:5], v[78:79], v[2:3] op_sel_hi:[1,0]
	v_pk_mul_f32 v[2:3], v[80:81], v[2:3] op_sel_hi:[1,0]
	v_pk_fma_f32 v[6:7], v[36:37], v[0:1], v[6:7] op_sel_hi:[1,0,1]
	v_pk_fma_f32 v[2:3], v[64:65], v[0:1], v[2:3] op_sel_hi:[1,0,1]
	v_pk_fma_f32 v[4:5], v[62:63], v[0:1], v[4:5] op_sel_hi:[1,0,1]
	v_pk_fma_f32 v[8:9], v[60:61], v[0:1], v[8:9] op_sel_hi:[1,0,1]
	v_pk_fma_f32 v[10:11], v[58:59], v[0:1], v[10:11] op_sel_hi:[1,0,1]
	v_pk_fma_f32 v[12:13], v[56:57], v[0:1], v[12:13] op_sel_hi:[1,0,1]
	v_pk_fma_f32 v[14:15], v[54:55], v[0:1], v[14:15] op_sel_hi:[1,0,1]
	v_pk_fma_f32 v[16:17], v[52:53], v[0:1], v[16:17] op_sel_hi:[1,0,1]
	v_pk_fma_f32 v[18:19], v[50:51], v[0:1], v[18:19] op_sel_hi:[1,0,1]
	v_lshlrev_b32_e32 v0, 3, v208
	v_lshl_add_u64 v[24:25], v[24:25], 0, v[0:1]
	global_load_dwordx2 v[98:99], v[24:25], off
	global_load_dwordx2 v[100:101], v[24:25], off offset:16
	global_load_dwordx2 v[102:103], v[24:25], off offset:32
	global_load_dwordx2 v[104:105], v[24:25], off offset:48
	global_load_dwordx2 v[106:107], v[24:25], off offset:64
	global_load_dwordx2 v[108:109], v[24:25], off offset:80
	global_load_dwordx2 v[110:111], v[24:25], off offset:96
	global_load_dwordx2 v[112:113], v[24:25], off offset:112
	s_waitcnt vmcnt(7)
	v_lshlrev_b32_e32 v38, 16, v98
	v_and_b32_e32 v39, 0xffff0000, v98
	v_lshlrev_b32_e32 v36, 16, v99
	v_and_b32_e32 v37, 0xffff0000, v99
	v_pk_add_f32 v[34:35], v[34:35], v[38:39]
	v_pk_add_f32 v[6:7], v[6:7], v[36:37]
	v_cvt_pk_bf16_f32 v34, v34, v35
	v_cvt_pk_bf16_f32 v35, v6, v7
	v_lshl_add_u64 v[6:7], v[178:179], 0, v[0:1]
	global_store_dwordx2 v[6:7], v[34:35], off
	s_waitcnt vmcnt(7)
	v_lshlrev_b32_e32 v36, 16, v100
	v_and_b32_e32 v37, 0xffff0000, v100
	v_lshlrev_b32_e32 v34, 16, v101
	v_and_b32_e32 v35, 0xffff0000, v101
	v_pk_add_f32 v[32:33], v[32:33], v[36:37]
	v_pk_add_f32 v[30:31], v[30:31], v[34:35]
	v_cvt_pk_bf16_f32 v32, v32, v33
	v_cvt_pk_bf16_f32 v33, v30, v31
	global_store_dwordx2 v[6:7], v[32:33], off offset:16
	s_waitcnt vmcnt(7)
	v_lshlrev_b32_e32 v32, 16, v102
	v_and_b32_e32 v33, 0xffff0000, v102
	v_lshlrev_b32_e32 v30, 16, v103
	v_and_b32_e32 v31, 0xffff0000, v103
	v_pk_add_f32 v[28:29], v[28:29], v[32:33]
	v_pk_add_f32 v[26:27], v[26:27], v[30:31]
	v_cvt_pk_bf16_f32 v28, v28, v29
	v_cvt_pk_bf16_f32 v29, v26, v27
	global_store_dwordx2 v[6:7], v[28:29], off offset:32
	s_waitcnt vmcnt(7)
	v_lshlrev_b32_e32 v28, 16, v104
	v_and_b32_e32 v29, 0xffff0000, v104
	v_lshlrev_b32_e32 v26, 16, v105
	v_and_b32_e32 v27, 0xffff0000, v105
	v_pk_add_f32 v[22:23], v[22:23], v[28:29]
	v_pk_add_f32 v[20:21], v[20:21], v[26:27]
	v_cvt_pk_bf16_f32 v22, v22, v23
	v_cvt_pk_bf16_f32 v23, v20, v21
	global_store_dwordx2 v[6:7], v[22:23], off offset:48
	s_waitcnt vmcnt(7)
	v_lshlrev_b32_e32 v22, 16, v106
	v_and_b32_e32 v23, 0xffff0000, v106
	v_lshlrev_b32_e32 v20, 16, v107
	v_and_b32_e32 v21, 0xffff0000, v107
	v_pk_add_f32 v[18:19], v[18:19], v[22:23]
	v_pk_add_f32 v[16:17], v[16:17], v[20:21]
	v_cvt_pk_bf16_f32 v18, v18, v19
	v_cvt_pk_bf16_f32 v19, v16, v17
	global_store_dwordx2 v[6:7], v[18:19], off offset:64
	s_waitcnt vmcnt(7)
	v_lshlrev_b32_e32 v18, 16, v108
	v_and_b32_e32 v19, 0xffff0000, v108
	v_lshlrev_b32_e32 v16, 16, v109
	v_and_b32_e32 v17, 0xffff0000, v109
	v_pk_add_f32 v[14:15], v[14:15], v[18:19]
	v_pk_add_f32 v[12:13], v[12:13], v[16:17]
	v_cvt_pk_bf16_f32 v14, v14, v15
	v_cvt_pk_bf16_f32 v15, v12, v13
	global_store_dwordx2 v[6:7], v[14:15], off offset:80
	s_waitcnt vmcnt(7)
	v_lshlrev_b32_e32 v14, 16, v110
	v_and_b32_e32 v15, 0xffff0000, v110
	v_lshlrev_b32_e32 v12, 16, v111
	v_and_b32_e32 v13, 0xffff0000, v111
	v_pk_add_f32 v[10:11], v[10:11], v[14:15]
	v_pk_add_f32 v[8:9], v[8:9], v[12:13]
	v_cvt_pk_bf16_f32 v10, v10, v11
	v_cvt_pk_bf16_f32 v11, v8, v9
	global_store_dwordx2 v[6:7], v[10:11], off offset:96
	s_waitcnt vmcnt(7)
	v_lshlrev_b32_e32 v10, 16, v112
	v_and_b32_e32 v11, 0xffff0000, v112
	v_lshlrev_b32_e32 v8, 16, v113
	v_and_b32_e32 v9, 0xffff0000, v113
	v_pk_add_f32 v[4:5], v[4:5], v[10:11]
	v_pk_add_f32 v[2:3], v[2:3], v[8:9]
	v_cvt_pk_bf16_f32 v4, v4, v5
	v_cvt_pk_bf16_f32 v5, v2, v3
	global_store_dwordx2 v[6:7], v[4:5], off offset:112

.LBB0_498:
	s_mov_b64 s[0:1], -1
	s_and_b64 vcc, exec, s[20:21]
	s_cbranch_vccz .LBB0_500
	v_mov_b32_e32 v2, v222
	v_and_b32_e32 v7, 64, v228
	v_and_b32_e32 v3, 63, v2
	v_lshlrev_b32_e32 v3, 2, v3
	global_load_dword v4, v3, s[8:9]
	global_load_dword v5, v3, s[8:9] offset:256
	v_add_u32_e32 v7, 64, v7
	v_xor_b32_e32 v8, 32, v228
	v_cmp_lt_i32_e32 vcc, v8, v7
	s_movk_i32 s0, 0x3000
	v_mov_b32_e32 v132, v44
	v_cndmask_b32_e32 v8, v228, v8, vcc
	s_waitcnt vmcnt(2)
	v_lshlrev_b32_e32 v166, 2, v8
	v_mov_b32_e32 v133, v42
	v_ashrrev_i32_e32 v0, 1, v2
	v_and_b32_e32 v0, 0xffffffe0, v0
	v_add_u32_e32 v0, s46, v0
	s_waitcnt vmcnt(0)
	v_mul_f32_e32 v6, v4, v5
	ds_bpermute_b32 v6, v166, v6
	s_waitcnt lgkmcnt(0)
	v_fmac_f32_e32 v6, v4, v5
	v_xor_b32_e32 v4, 16, v228
	v_cmp_lt_i32_e32 vcc, v4, v7
	s_nop 1
	v_cndmask_b32_e32 v4, v228, v4, vcc
	v_lshlrev_b32_e32 v4, 2, v4
	ds_bpermute_b32 v5, v4, v6
	s_waitcnt lgkmcnt(0)
	v_add_f32_e32 v5, v6, v5
	v_xor_b32_e32 v6, 8, v228
	v_cmp_lt_i32_e32 vcc, v6, v7
	s_nop 1
	v_cndmask_b32_e32 v6, v228, v6, vcc
	v_lshlrev_b32_e32 v6, 2, v6
	ds_bpermute_b32 v8, v6, v5
	s_waitcnt lgkmcnt(0)
	v_add_f32_e32 v5, v5, v8
	v_xor_b32_e32 v8, 4, v228
	v_cmp_lt_i32_e32 vcc, v8, v7
	s_nop 1
	v_cndmask_b32_e32 v8, v228, v8, vcc
	v_lshlrev_b32_e32 v8, 2, v8
	ds_bpermute_b32 v9, v8, v5
	s_waitcnt lgkmcnt(0)
	v_add_f32_e32 v5, v5, v9
	v_xor_b32_e32 v9, 2, v228
	v_cmp_lt_i32_e32 vcc, v9, v7
	s_nop 1
	v_cndmask_b32_e32 v9, v228, v9, vcc
	v_lshlrev_b32_e32 v9, 2, v9
	ds_bpermute_b32 v10, v9, v5
	s_waitcnt lgkmcnt(0)
	v_add_f32_e32 v5, v5, v10
	v_xor_b32_e32 v10, 1, v228
	v_cmp_lt_i32_e32 vcc, v10, v7
	s_nop 1
	v_cndmask_b32_e32 v7, v228, v10, vcc
	v_lshlrev_b32_e32 v7, 2, v7
	ds_bpermute_b32 v10, v7, v5
	s_waitcnt lgkmcnt(0)
	v_add_f32_e32 v5, v5, v10
	global_load_dword v10, v3, s[8:9] offset:512
	s_nop 0
	global_load_dword v3, v3, s[8:9] offset:768
	s_waitcnt vmcnt(0)
	v_mul_f32_e32 v11, v10, v3
	ds_bpermute_b32 v11, v166, v11
	s_waitcnt lgkmcnt(0)
	v_fmac_f32_e32 v11, v10, v3
	ds_bpermute_b32 v3, v4, v11
	s_waitcnt lgkmcnt(0)
	v_add_f32_e32 v3, v11, v3
	ds_bpermute_b32 v4, v6, v3
	s_waitcnt lgkmcnt(0)
	v_add_f32_e32 v3, v3, v4
	ds_bpermute_b32 v4, v8, v3
	s_waitcnt lgkmcnt(0)
	v_add_f32_e32 v3, v3, v4
	ds_bpermute_b32 v4, v9, v3
	s_waitcnt lgkmcnt(0)
	v_add_f32_e32 v3, v3, v4
	ds_bpermute_b32 v4, v7, v3
	s_waitcnt lgkmcnt(0)
	v_add_f32_e32 v3, v3, v4
	v_mul_f32_e32 v4, 0x3fb8aa3b, v5
	v_mul_f32_e32 v3, 0x3fb8aa3b, v3
	v_exp_f32_e32 v4, v4
	v_exp_f32_e32 v3, v3
	s_nop 0
	v_sub_f32_e32 v3, v4, v3
	ds_bpermute_b32 v4, v166, v203
	v_add_f32_e32 v3, v211, v3
	s_waitcnt lgkmcnt(0)
	v_add_f32_e32 v4, v203, v4
	v_rcp_f32_e32 v4, v4
	s_nop 0
	v_mul_f32_e32 v6, v4, v3
	v_ashrrev_i32_e32 v3, 31, v2
	v_lshl_add_u64 v[4:5], v[2:3], 2, s[10:11]
	global_load_dword v134, v[4:5], off
	v_add_co_u32_e32 v8, vcc, s65, v4
	global_load_dword v135, v[4:5], off offset:1024
	s_nop 1
	v_addc_co_u32_e32 v9, vcc, 0, v5, vcc
	v_add_co_u32_e32 v10, vcc, s57, v4
	global_load_dword v136, v[4:5], off offset:2048
	s_nop 1
	v_addc_co_u32_e32 v11, vcc, 0, v5, vcc
	global_load_dword v137, v[4:5], off offset:3072
	global_load_dword v138, v[10:11], off offset:-4096
	global_load_dword v139, v[8:9], off offset:1024
	global_load_dword v140, v[8:9], off offset:2048
	global_load_dword v141, v[8:9], off offset:3072
	v_add_co_u32_e32 v8, vcc, s0, v4
	s_movk_i32 s0, 0x7000
	s_nop 0
	s_nop 1
	v_addc_co_u32_e32 v9, vcc, 0, v5, vcc
	global_load_dword v142, v[10:11], off
	global_load_dword v143, v[10:11], off offset:1024
	global_load_dword v144, v[10:11], off offset:2048
	global_load_dword v145, v[10:11], off offset:3072
	v_add_co_u32_e32 v10, vcc, s62, v4
	s_nop 1
	v_addc_co_u32_e32 v11, vcc, 0, v5, vcc
	global_load_dword v146, v[10:11], off offset:-4096
	global_load_dword v147, v[8:9], off offset:1024
	global_load_dword v148, v[8:9], off offset:2048
	global_load_dword v149, v[8:9], off offset:3072
	v_add_co_u32_e32 v8, vcc, s64, v4
	global_load_dword v150, v[10:11], off
	s_nop 1
	v_addc_co_u32_e32 v9, vcc, 0, v5, vcc
	global_load_dword v151, v[10:11], off offset:1024
	global_load_dword v152, v[10:11], off offset:2048
	global_load_dword v153, v[10:11], off offset:3072
	v_add_co_u32_e32 v10, vcc, s88, v4
	s_nop 1
	v_addc_co_u32_e32 v11, vcc, 0, v5, vcc
	global_load_dword v154, v[10:11], off offset:-4096
	v_add_co_u32_e32 v4, vcc, s0, v4
	s_mov_b64 s[0:1], 0
	s_nop 0
	s_nop 1
	v_addc_co_u32_e32 v5, vcc, 0, v5, vcc
	global_load_dword v155, v[8:9], off offset:1024
	global_load_dword v156, v[8:9], off offset:2048
	global_load_dword v157, v[8:9], off offset:3072
	global_load_dword v158, v[10:11], off
	global_load_dword v159, v[10:11], off offset:1024
	global_load_dword v160, v[10:11], off offset:2048
	global_load_dword v161, v[10:11], off offset:3072
	s_waitcnt vmcnt(0)
	v_lshlrev_b32_e32 v16, 16, v134
	v_and_b32_e32 v17, 0xffff0000, v134
	v_lshlrev_b32_e32 v30, 16, v135
	v_and_b32_e32 v31, 0xffff0000, v135
	v_lshlrev_b32_e32 v12, 16, v136
	v_and_b32_e32 v13, 0xffff0000, v136
	v_lshlrev_b32_e32 v28, 16, v137
	v_and_b32_e32 v29, 0xffff0000, v137
	v_lshlrev_b32_e32 v26, 16, v138
	v_and_b32_e32 v27, 0xffff0000, v138
	v_lshlrev_b32_e32 v98, 16, v139
	v_and_b32_e32 v99, 0xffff0000, v139
	v_lshlrev_b32_e32 v22, 16, v140
	v_and_b32_e32 v23, 0xffff0000, v140
	v_lshlrev_b32_e32 v32, 16, v141
	v_and_b32_e32 v33, 0xffff0000, v141
	v_lshlrev_b32_e32 v18, 16, v142
	v_and_b32_e32 v19, 0xffff0000, v142
	v_lshlrev_b32_e32 v24, 16, v143
	v_and_b32_e32 v25, 0xffff0000, v143
	v_lshlrev_b32_e32 v14, 16, v144
	v_and_b32_e32 v15, 0xffff0000, v144
	v_lshlrev_b32_e32 v20, 16, v145
	v_and_b32_e32 v21, 0xffff0000, v145
	v_lshlrev_b32_e32 v110, 16, v146
	v_and_b32_e32 v111, 0xffff0000, v146
	v_lshlrev_b32_e32 v114, 16, v147
	v_and_b32_e32 v115, 0xffff0000, v147
	v_lshlrev_b32_e32 v106, 16, v148
	v_and_b32_e32 v107, 0xffff0000, v148
	v_lshlrev_b32_e32 v112, 16, v149
	v_and_b32_e32 v113, 0xffff0000, v149
	v_lshlrev_b32_e32 v102, 16, v150
	v_and_b32_e32 v103, 0xffff0000, v150
	v_lshlrev_b32_e32 v108, 16, v151
	v_and_b32_e32 v109, 0xffff0000, v151
	v_lshlrev_b32_e32 v100, 16, v152
	v_and_b32_e32 v101, 0xffff0000, v152
	v_lshlrev_b32_e32 v104, 16, v153
	v_and_b32_e32 v105, 0xffff0000, v153
	v_lshlrev_b32_e32 v126, 16, v154
	v_and_b32_e32 v127, 0xffff0000, v154
	v_lshlrev_b32_e32 v130, 16, v155
	v_and_b32_e32 v131, 0xffff0000, v155
	v_lshlrev_b32_e32 v124, 16, v156
	v_and_b32_e32 v125, 0xffff0000, v156
	v_lshlrev_b32_e32 v128, 16, v157
	v_and_b32_e32 v129, 0xffff0000, v157
	v_lshlrev_b32_e32 v120, 16, v158
	v_and_b32_e32 v121, 0xffff0000, v158
	v_lshlrev_b32_e32 v122, 16, v159
	v_and_b32_e32 v123, 0xffff0000, v159
	v_lshlrev_b32_e32 v116, 16, v160
	v_and_b32_e32 v117, 0xffff0000, v160
	v_lshlrev_b32_e32 v118, 16, v161
	v_and_b32_e32 v119, 0xffff0000, v161
	global_load_dword v3, v[4:5], off
	global_load_dword v7, v[4:5], off offset:1024
	s_waitcnt vmcnt(1)
	v_lshlrev_b32_e32 v9, 16, v3
	s_waitcnt vmcnt(0)
	v_lshlrev_b32_e32 v8, 16, v7
	v_and_b32_e32 v11, 0xffff0000, v3
	v_and_b32_e32 v10, 0xffff0000, v7
	v_pk_fma_f32 v[8:9], v[132:133], v[6:7], v[8:9] op_sel_hi:[1,0,1] neg_lo:[1,0,0] neg_hi:[1,0,0]
	v_mov_b32_e32 v132, v45
	v_mov_b32_e32 v133, v43
	v_pk_fma_f32 v[10:11], v[132:133], v[6:7], v[10:11] op_sel_hi:[1,0,1] neg_lo:[1,0,0] neg_hi:[1,0,0]
	global_load_dword v3, v[4:5], off offset:2048
	global_load_dword v7, v[4:5], off offset:3072
	v_pk_mul_f32 v[132:133], v[10:11], v[10:11]
	s_waitcnt vmcnt(1)
	v_lshlrev_b32_e32 v5, 16, v3
	v_pk_fma_f32 v[136:137], v[8:9], v[8:9], v[132:133]
	s_waitcnt vmcnt(0)
	v_lshlrev_b32_e32 v4, 16, v7
	v_mov_b32_e32 v132, v48
	v_mov_b32_e32 v133, v46
	v_and_b32_e32 v135, 0xffff0000, v3
	v_and_b32_e32 v134, 0xffff0000, v7
	v_pk_fma_f32 v[132:133], v[132:133], v[6:7], v[4:5] op_sel_hi:[1,0,1] neg_lo:[1,0,0] neg_hi:[1,0,0]
	v_mov_b32_e32 v4, v49
	v_mov_b32_e32 v5, v47
	v_pk_fma_f32 v[134:135], v[4:5], v[6:7], v[134:135] op_sel_hi:[1,0,1] neg_lo:[1,0,0] neg_hi:[1,0,0]
	v_pk_fma_f32 v[144:145], v[68:69], v[6:7], v[24:25] op_sel_hi:[1,0,1] neg_lo:[1,0,0] neg_hi:[1,0,0]
	v_pk_mul_f32 v[4:5], v[134:135], v[134:135]
	v_pk_fma_f32 v[148:149], v[66:67], v[6:7], v[18:19] op_sel_hi:[1,0,1] neg_lo:[1,0,0] neg_hi:[1,0,0]
	v_pk_fma_f32 v[154:155], v[132:133], v[132:133], v[4:5]
	v_and_or_b32 v4, v2, 31, v0
	v_ashrrev_i32_e32 v5, 31, v4
	v_lshrrev_b32_e32 v0, 3, v2
	v_lshl_add_u64 v[4:5], s[60:61], 0, v[4:5]
	v_and_b32_e32 v0, 4, v0
	v_lshlrev_b64 v[4:5], 10, v[4:5]
	v_lshlrev_b32_e32 v167, 2, v0
	v_lshl_add_u64 v[138:139], s[14:15], 0, v[4:5]
	global_load_dwordx4 v[2:5], v167, s[12:13]
	v_pk_fma_f32 v[18:19], v[64:65], v[6:7], v[128:129] op_sel_hi:[1,0,1] neg_lo:[1,0,0] neg_hi:[1,0,0]
	v_pk_fma_f32 v[24:25], v[62:63], v[6:7], v[124:125] op_sel_hi:[1,0,1] neg_lo:[1,0,0] neg_hi:[1,0,0]
	v_pk_fma_f32 v[142:143], v[70:71], v[6:7], v[14:15] op_sel_hi:[1,0,1] neg_lo:[1,0,0] neg_hi:[1,0,0]
	v_mov_b32_e32 v14, v19
	v_mov_b32_e32 v15, v25
	v_lshlrev_b32_e32 v0, 1, v0
	v_pk_fma_f32 v[160:161], v[86:87], v[6:7], v[12:13] op_sel_hi:[1,0,1] neg_lo:[1,0,0] neg_hi:[1,0,0]
	v_mov_b32_e32 v12, v18
	v_mov_b32_e32 v13, v24
	v_pk_mul_f32 v[14:15], v[14:15], v[14:15]
	v_pk_fma_f32 v[152:153], v[82:83], v[6:7], v[16:17] op_sel_hi:[1,0,1] neg_lo:[1,0,0] neg_hi:[1,0,0]
	v_lshl_add_u64 v[16:17], v[138:139], 0, v[0:1]
	v_pk_fma_f32 v[138:139], v[72:73], v[6:7], v[20:21] op_sel_hi:[1,0,1] neg_lo:[1,0,0] neg_hi:[1,0,0]
	v_pk_fma_f32 v[124:125], v[12:13], v[12:13], v[14:15]
	v_pk_fma_f32 v[14:15], v[36:37], v[6:7], v[122:123] op_sel_hi:[1,0,1] neg_lo:[1,0,0] neg_hi:[1,0,0]
	v_pk_fma_f32 v[20:21], v[34:35], v[6:7], v[120:121] op_sel_hi:[1,0,1] neg_lo:[1,0,0] neg_hi:[1,0,0]
	v_mov_b32_e32 v120, v15
	v_mov_b32_e32 v121, v21
	v_mov_b32_e32 v12, v14
	v_mov_b32_e32 v13, v20
	v_pk_mul_f32 v[120:121], v[120:121], v[120:121]
	v_pk_fma_f32 v[146:147], v[84:85], v[6:7], v[30:31] op_sel_hi:[1,0,1] neg_lo:[1,0,0] neg_hi:[1,0,0]
	v_pk_fma_f32 v[156:157], v[88:89], v[6:7], v[28:29] op_sel_hi:[1,0,1] neg_lo:[1,0,0] neg_hi:[1,0,0]
	v_pk_fma_f32 v[158:159], v[92:93], v[6:7], v[98:99] op_sel_hi:[1,0,1] neg_lo:[1,0,0] neg_hi:[1,0,0]
	v_pk_fma_f32 v[162:163], v[90:91], v[6:7], v[26:27] op_sel_hi:[1,0,1] neg_lo:[1,0,0] neg_hi:[1,0,0]
	v_pk_fma_f32 v[150:151], v[96:97], v[6:7], v[32:33] op_sel_hi:[1,0,1] neg_lo:[1,0,0] neg_hi:[1,0,0]
	v_pk_fma_f32 v[164:165], v[94:95], v[6:7], v[22:23] op_sel_hi:[1,0,1] neg_lo:[1,0,0] neg_hi:[1,0,0]
	v_pk_fma_f32 v[114:115], v[76:77], v[6:7], v[114:115] op_sel_hi:[1,0,1] neg_lo:[1,0,0] neg_hi:[1,0,0]
	v_pk_fma_f32 v[140:141], v[74:75], v[6:7], v[110:111] op_sel_hi:[1,0,1] neg_lo:[1,0,0] neg_hi:[1,0,0]
	v_pk_fma_f32 v[110:111], v[80:81], v[6:7], v[112:113] op_sel_hi:[1,0,1] neg_lo:[1,0,0] neg_hi:[1,0,0]
	v_pk_fma_f32 v[106:107], v[78:79], v[6:7], v[106:107] op_sel_hi:[1,0,1] neg_lo:[1,0,0] neg_hi:[1,0,0]
	v_pk_fma_f32 v[32:33], v[52:53], v[6:7], v[108:109] op_sel_hi:[1,0,1] neg_lo:[1,0,0] neg_hi:[1,0,0]
	v_pk_fma_f32 v[98:99], v[50:51], v[6:7], v[102:103] op_sel_hi:[1,0,1] neg_lo:[1,0,0] neg_hi:[1,0,0]
	v_pk_fma_f32 v[26:27], v[56:57], v[6:7], v[104:105] op_sel_hi:[1,0,1] neg_lo:[1,0,0] neg_hi:[1,0,0]
	v_pk_fma_f32 v[30:31], v[54:55], v[6:7], v[100:101] op_sel_hi:[1,0,1] neg_lo:[1,0,0] neg_hi:[1,0,0]
	v_pk_fma_f32 v[22:23], v[60:61], v[6:7], v[130:131] op_sel_hi:[1,0,1] neg_lo:[1,0,0] neg_hi:[1,0,0]
	v_pk_fma_f32 v[28:29], v[58:59], v[6:7], v[126:127] op_sel_hi:[1,0,1] neg_lo:[1,0,0] neg_hi:[1,0,0]
	v_pk_fma_f32 v[120:121], v[12:13], v[12:13], v[120:121]
	v_pk_fma_f32 v[12:13], v[40:41], v[6:7], v[118:119] op_sel_hi:[1,0,1] neg_lo:[1,0,0] neg_hi:[1,0,0]
	v_pk_fma_f32 v[6:7], v[38:39], v[6:7], v[116:117] op_sel_hi:[1,0,1] neg_lo:[1,0,0] neg_hi:[1,0,0]
	v_mov_b32_e32 v118, v13
	v_mov_b32_e32 v119, v7
	v_pk_mul_f32 v[168:169], v[146:147], v[146:147]
	v_pk_mul_f32 v[170:171], v[152:153], v[152:153]
	v_mov_b32_e32 v116, v12
	v_mov_b32_e32 v117, v6
	v_pk_mul_f32 v[118:119], v[118:119], v[118:119]
	v_pk_mul_f32 v[174:175], v[160:161], v[160:161]
	v_pk_fma_f32 v[116:117], v[116:117], v[116:117], v[118:119]
	v_add_f32_e32 v0, v168, v169
	v_add_f32_e32 v118, v170, v171
	v_pk_mul_f32 v[172:173], v[156:157], v[156:157]
	v_add_f32_e32 v0, v118, v0
	v_add_f32_e32 v118, v174, v175
	v_pk_mul_f32 v[178:179], v[162:163], v[162:163]
	v_add_f32_e32 v0, v118, v0
	v_add_f32_e32 v118, v172, v173
	v_pk_mul_f32 v[176:177], v[158:159], v[158:159]
	v_add_f32_e32 v0, v118, v0
	v_add_f32_e32 v118, v178, v179
	v_pk_mul_f32 v[182:183], v[164:165], v[164:165]
	v_add_f32_e32 v0, v118, v0
	v_add_f32_e32 v118, v176, v177
	v_pk_mul_f32 v[180:181], v[150:151], v[150:151]
	v_add_f32_e32 v0, v118, v0
	v_add_f32_e32 v118, v182, v183
	v_pk_mul_f32 v[186:187], v[148:149], v[148:149]
	v_add_f32_e32 v0, v118, v0
	v_add_f32_e32 v118, v180, v181
	v_pk_mul_f32 v[184:185], v[144:145], v[144:145]
	v_add_f32_e32 v0, v118, v0
	v_add_f32_e32 v118, v186, v187
	v_pk_mul_f32 v[190:191], v[142:143], v[142:143]
	v_add_f32_e32 v0, v118, v0
	v_add_f32_e32 v118, v184, v185
	v_pk_mul_f32 v[188:189], v[138:139], v[138:139]
	v_add_f32_e32 v0, v118, v0
	v_add_f32_e32 v118, v190, v191
	v_pk_mul_f32 v[194:195], v[140:141], v[140:141]
	v_add_f32_e32 v0, v118, v0
	v_add_f32_e32 v118, v188, v189
	v_pk_mul_f32 v[192:193], v[114:115], v[114:115]
	v_add_f32_e32 v0, v118, v0
	v_add_f32_e32 v118, v194, v195
	v_pk_mul_f32 v[196:197], v[106:107], v[106:107]
	v_add_f32_e32 v0, v118, v0
	v_add_f32_e32 v118, v192, v193
	v_pk_mul_f32 v[112:113], v[110:111], v[110:111]
	v_add_f32_e32 v0, v118, v0
	v_add_f32_e32 v118, v196, v197
	v_pk_mul_f32 v[102:103], v[98:99], v[98:99]
	v_add_f32_e32 v0, v118, v0
	v_add_f32_e32 v112, v112, v113
	v_pk_mul_f32 v[108:109], v[32:33], v[32:33]
	v_add_f32_e32 v0, v112, v0
	v_add_f32_e32 v102, v102, v103
	v_pk_mul_f32 v[100:101], v[30:31], v[30:31]
	v_add_f32_e32 v0, v102, v0
	v_add_f32_e32 v102, v108, v109
	v_pk_mul_f32 v[104:105], v[26:27], v[26:27]
	v_add_f32_e32 v0, v102, v0
	v_add_f32_e32 v100, v100, v101
	v_pk_mul_f32 v[126:127], v[28:29], v[28:29]
	v_add_f32_e32 v0, v100, v0
	v_add_f32_e32 v100, v104, v105
	v_pk_mul_f32 v[130:131], v[22:23], v[22:23]
	v_add_f32_e32 v0, v100, v0
	v_add_f32_e32 v100, v126, v127
	v_add_f32_e32 v0, v100, v0
	v_add_f32_e32 v100, v130, v131
	v_add_f32_e32 v0, v100, v0
	v_add_f32_e32 v0, v125, v0
	v_add_f32_e32 v0, v124, v0
	v_add_f32_e32 v0, v121, v0
	v_add_f32_e32 v0, v120, v0
	v_add_f32_e32 v0, v117, v0
	v_add_f32_e32 v0, v116, v0
	v_add_f32_e32 v0, v137, v0
	v_add_f32_e32 v0, v136, v0
	v_add_f32_e32 v0, v155, v0
	v_add_f32_e32 v0, v154, v0
	ds_bpermute_b32 v100, v166, v0
	s_waitcnt lgkmcnt(0)
	v_add_f32_e32 v0, v0, v100
	v_fmamk_f32 v0, v0, 0x3c000000, v224
	v_cmp_gt_f32_e32 vcc, s59, v0
	v_mul_f32_e32 v100, 0x4b800000, v0
	s_nop 0
	v_cndmask_b32_e32 v0, v0, v100, vcc
	v_rsq_f32_e32 v0, v0
	s_nop 0
	v_mul_f32_e32 v100, 0x45800000, v0
	v_cndmask_b32_e32 v0, v0, v100, vcc
	v_sub_f32_e32 v100, 1.0, v211
	v_mul_f32_e32 v0, v100, v0
	v_pk_mul_f32 v[100:101], v[152:153], v[0:1] op_sel_hi:[1,0]
	v_pk_mul_f32 v[98:99], v[98:99], v[0:1] op_sel_hi:[1,0]
	global_load_dwordx4 v[168:171], v167, s[12:13] offset:32
	global_load_dwordx4 v[172:175], v167, s[12:13] offset:64
	global_load_dwordx4 v[176:179], v167, s[12:13] offset:96
	global_load_dwordx4 v[180:183], v167, s[12:13] offset:128
	global_load_dwordx4 v[184:187], v167, s[12:13] offset:160
	global_load_dwordx4 v[188:191], v167, s[12:13] offset:192
	global_load_dwordx4 v[192:195], v167, s[12:13] offset:224
	global_load_dwordx4 v[196:199], v167, s[12:13] offset:256
	s_waitcnt vmcnt(8)
	v_pk_mul_f32 v[2:3], v[2:3], v[100:101]
	v_pk_mul_f32 v[100:101], v[146:147], v[0:1] op_sel_hi:[1,0]
	v_cvt_pk_bf16_f32 v2, v2, v3
	v_pk_mul_f32 v[4:5], v[4:5], v[100:101]
	v_pk_mul_f32 v[100:101], v[160:161], v[0:1] op_sel_hi:[1,0]
	v_cvt_pk_bf16_f32 v3, v4, v5
	global_store_dwordx2 v[16:17], v[2:3], off
	v_pk_mul_f32 v[32:33], v[32:33], v[0:1] op_sel_hi:[1,0]
	v_pk_mul_f32 v[30:31], v[30:31], v[0:1] op_sel_hi:[1,0]
	v_pk_mul_f32 v[26:27], v[26:27], v[0:1] op_sel_hi:[1,0]
	v_pk_mul_f32 v[22:23], v[22:23], v[0:1] op_sel_hi:[1,0]
	v_pk_mul_f32 v[18:19], v[18:19], v[0:1] op_sel_hi:[1,0]
	v_pk_mul_f32 v[14:15], v[14:15], v[0:1] op_sel_hi:[1,0]
	v_pk_mul_f32 v[6:7], v[6:7], v[0:1] op_sel_hi:[1,0]
	s_waitcnt vmcnt(8)
	v_pk_mul_f32 v[2:3], v[168:169], v[100:101]
	v_pk_mul_f32 v[100:101], v[156:157], v[0:1] op_sel_hi:[1,0]
	v_cvt_pk_bf16_f32 v2, v2, v3
	v_pk_mul_f32 v[4:5], v[170:171], v[100:101]
	v_pk_mul_f32 v[100:101], v[162:163], v[0:1] op_sel_hi:[1,0]
	v_cvt_pk_bf16_f32 v3, v4, v5
	global_store_dwordx2 v[16:17], v[2:3], off offset:16
	global_load_dwordx4 v[168:171], v167, s[12:13] offset:288
	s_waitcnt vmcnt(9)
	v_pk_mul_f32 v[2:3], v[172:173], v[100:101]
	v_pk_mul_f32 v[100:101], v[158:159], v[0:1] op_sel_hi:[1,0]
	v_cvt_pk_bf16_f32 v2, v2, v3
	v_pk_mul_f32 v[4:5], v[174:175], v[100:101]
	v_pk_mul_f32 v[100:101], v[164:165], v[0:1] op_sel_hi:[1,0]
	v_cvt_pk_bf16_f32 v3, v4, v5
	global_store_dwordx2 v[16:17], v[2:3], off offset:32
	global_load_dwordx4 v[172:175], v167, s[12:13] offset:320
	s_waitcnt vmcnt(10)
	v_pk_mul_f32 v[2:3], v[176:177], v[100:101]
	v_pk_mul_f32 v[100:101], v[150:151], v[0:1] op_sel_hi:[1,0]
	v_cvt_pk_bf16_f32 v2, v2, v3
	v_pk_mul_f32 v[4:5], v[178:179], v[100:101]
	v_pk_mul_f32 v[100:101], v[148:149], v[0:1] op_sel_hi:[1,0]
	v_cvt_pk_bf16_f32 v3, v4, v5
	global_store_dwordx2 v[16:17], v[2:3], off offset:48
	global_load_dwordx4 v[176:179], v167, s[12:13] offset:352
	s_waitcnt vmcnt(11)
	v_pk_mul_f32 v[2:3], v[180:181], v[100:101]
	v_pk_mul_f32 v[100:101], v[144:145], v[0:1] op_sel_hi:[1,0]
	v_cvt_pk_bf16_f32 v2, v2, v3
	v_pk_mul_f32 v[4:5], v[182:183], v[100:101]
	v_pk_mul_f32 v[100:101], v[142:143], v[0:1] op_sel_hi:[1,0]
	v_cvt_pk_bf16_f32 v3, v4, v5
	global_store_dwordx2 v[16:17], v[2:3], off offset:64
	global_load_dwordx4 v[180:183], v167, s[12:13] offset:384
	s_waitcnt vmcnt(12)
	v_pk_mul_f32 v[2:3], v[184:185], v[100:101]
	v_pk_mul_f32 v[100:101], v[138:139], v[0:1] op_sel_hi:[1,0]
	v_cvt_pk_bf16_f32 v2, v2, v3
	v_pk_mul_f32 v[4:5], v[186:187], v[100:101]
	v_pk_mul_f32 v[100:101], v[140:141], v[0:1] op_sel_hi:[1,0]
	v_cvt_pk_bf16_f32 v3, v4, v5
	global_store_dwordx2 v[16:17], v[2:3], off offset:80
	global_load_dwordx4 v[184:187], v167, s[12:13] offset:416
	s_waitcnt vmcnt(13)
	v_pk_mul_f32 v[2:3], v[188:189], v[100:101]
	v_pk_mul_f32 v[100:101], v[114:115], v[0:1] op_sel_hi:[1,0]
	v_cvt_pk_bf16_f32 v2, v2, v3
	v_pk_mul_f32 v[4:5], v[190:191], v[100:101]
	v_pk_mul_f32 v[100:101], v[106:107], v[0:1] op_sel_hi:[1,0]
	v_cvt_pk_bf16_f32 v3, v4, v5
	global_store_dwordx2 v[16:17], v[2:3], off offset:96
	global_load_dwordx4 v[188:191], v167, s[12:13] offset:448
	s_waitcnt vmcnt(14)
	v_pk_mul_f32 v[2:3], v[192:193], v[100:101]
	v_pk_mul_f32 v[100:101], v[110:111], v[0:1] op_sel_hi:[1,0]
	v_cvt_pk_bf16_f32 v2, v2, v3
	v_pk_mul_f32 v[4:5], v[194:195], v[100:101]
	s_nop 0
	v_cvt_pk_bf16_f32 v3, v4, v5
	global_store_dwordx2 v[16:17], v[2:3], off offset:112
	global_load_dwordx4 v[192:195], v167, s[12:13] offset:480
	s_waitcnt vmcnt(15)
	v_pk_mul_f32 v[2:3], v[196:197], v[98:99]
	v_pk_mul_f32 v[4:5], v[198:199], v[32:33]
	v_cvt_pk_bf16_f32 v2, v2, v3
	v_cvt_pk_bf16_f32 v3, v4, v5
	global_store_dwordx2 v[16:17], v[2:3], off offset:128
	s_waitcnt vmcnt(13)
	v_pk_mul_f32 v[2:3], v[30:31], v[168:169]
	v_pk_mul_f32 v[4:5], v[26:27], v[170:171]
	v_cvt_pk_bf16_f32 v2, v2, v3
	v_cvt_pk_bf16_f32 v3, v4, v5
	global_store_dwordx2 v[16:17], v[2:3], off offset:144
	v_pk_mul_f32 v[26:27], v[28:29], v[0:1] op_sel_hi:[1,0]
	s_waitcnt vmcnt(12)
	v_pk_mul_f32 v[4:5], v[22:23], v[174:175]
	v_pk_mul_f32 v[2:3], v[26:27], v[172:173]
	v_pk_mul_f32 v[22:23], v[24:25], v[0:1] op_sel_hi:[1,0]
	v_cvt_pk_bf16_f32 v2, v2, v3
	v_cvt_pk_bf16_f32 v3, v4, v5
	global_store_dwordx2 v[16:17], v[2:3], off offset:160
	s_waitcnt vmcnt(11)
	v_pk_mul_f32 v[2:3], v[22:23], v[176:177]
	v_pk_mul_f32 v[4:5], v[18:19], v[178:179]
	v_cvt_pk_bf16_f32 v2, v2, v3
	v_cvt_pk_bf16_f32 v3, v4, v5
	global_store_dwordx2 v[16:17], v[2:3], off offset:176
	v_pk_mul_f32 v[18:19], v[20:21], v[0:1] op_sel_hi:[1,0]
	s_waitcnt vmcnt(10)
	v_pk_mul_f32 v[4:5], v[14:15], v[182:183]
	v_pk_mul_f32 v[2:3], v[18:19], v[180:181]
	s_nop 0
	v_cvt_pk_bf16_f32 v2, v2, v3
	v_cvt_pk_bf16_f32 v3, v4, v5
	global_store_dwordx2 v[16:17], v[2:3], off offset:192
	s_waitcnt vmcnt(9)
	v_pk_mul_f32 v[2:3], v[6:7], v[184:185]
	v_pk_mul_f32 v[6:7], v[12:13], v[0:1] op_sel_hi:[1,0]
	v_cvt_pk_bf16_f32 v2, v2, v3
	v_pk_mul_f32 v[4:5], v[6:7], v[186:187]
	v_mov_b32_e32 v6, v9
	v_cvt_pk_bf16_f32 v3, v4, v5
	global_store_dwordx2 v[16:17], v[2:3], off offset:208
	v_mov_b32_e32 v7, v11
	v_pk_mul_f32 v[6:7], v[6:7], v[0:1] op_sel_hi:[1,0]
	v_mov_b32_e32 v9, v10
	s_waitcnt vmcnt(8)
	v_pk_mul_f32 v[2:3], v[6:7], v[188:189]
	v_pk_mul_f32 v[6:7], v[8:9], v[0:1] op_sel_hi:[1,0]
	v_cvt_pk_bf16_f32 v2, v2, v3
	v_pk_mul_f32 v[4:5], v[6:7], v[190:191]
	v_mov_b32_e32 v6, v133
	v_cvt_pk_bf16_f32 v3, v4, v5
	global_store_dwordx2 v[16:17], v[2:3], off offset:224
	v_mov_b32_e32 v7, v135
	v_pk_mul_f32 v[6:7], v[6:7], v[0:1] op_sel_hi:[1,0]
	v_mov_b32_e32 v133, v134
	s_waitcnt vmcnt(7)
	v_pk_mul_f32 v[2:3], v[6:7], v[192:193]
	v_pk_mul_f32 v[6:7], v[132:133], v[0:1] op_sel_hi:[1,0]
	v_cvt_pk_bf16_f32 v2, v2, v3
	v_pk_mul_f32 v[4:5], v[6:7], v[194:195]
	s_nop 0
	v_cvt_pk_bf16_f32 v3, v4, v5
	global_store_dwordx2 v[16:17], v[2:3], off offset:240
